# norm1 context rows: split-K partial sums loaded in batches of 12 instead of 44 serial round trips
# speedup vs baseline: 1.0060x; 1.0035x over previous
.LBB0_276:
	v_readlane_b32 s6, v255, 12
	v_readlane_b32 s7, v255, 13
	v_add_u32_e32 v128, 0xffffc000, v20
	v_ashrrev_i32_e32 v21, 31, v20
	v_cmp_gt_i32_e32 vcc, s33, v20
	v_mov_b32_e32 v2, s7
	v_readlane_b32 s4, v255, 16
	v_cndmask_b32_e32 v1, 0, v21, vcc
	v_cndmask_b32_e32 v0, v128, v20, vcc
	v_cndmask_b32_e32 v3, v72, v2, vcc
	v_mov_b32_e32 v2, s4
	v_mov_b32_e32 v4, s6
	v_cndmask_b32_e32 v2, v2, v4, vcc
	v_lshlrev_b64 v[0:1], 12, v[0:1]
	v_lshl_add_u64 v[0:1], v[2:3], 0, v[0:1]
	v_mov_b32_e32 v39, v129
	v_lshl_add_u64 v[0:1], v[0:1], 0, v[38:39]
	global_load_dwordx4 v[12:15], v[0:1], off
	global_load_dwordx4 v[8:11], v[0:1], off offset:1024
	global_load_dwordx4 v[4:7], v[0:1], off offset:2048
	s_nop 0
	global_load_dwordx4 v[0:3], v[0:1], off offset:3072
	s_movk_i32 s4, 0x3fff
	v_readlane_b32 s5, v255, 17
	v_cmp_lt_i32_e32 vcc, s4, v20
	s_and_b64 s[4:5], s[0:1], vcc
	s_and_saveexec_b64 s[42:43], s[4:5]
	s_cbranch_execz .LBB0_275
	v_lshlrev_b64 v[16:17], 12, v[128:129]
	v_lshl_add_u64 v[48:49], v[32:33], 0, v[16:17]
	v_lshlrev_b64 v[46:47], 12, v[20:21]
	v_lshl_add_u64 v[46:47], v[34:35], 0, v[46:47]
	v_add_co_u32_e32 v16, vcc, 0x200000, v48
	s_nop 1
	v_addc_co_u32_e32 v17, vcc, 0, v49, vcc
	v_add_co_u32_e32 v18, vcc, 0x400000, v48
	s_nop 1
	v_addc_co_u32_e32 v19, vcc, 0, v49, vcc
	v_add_co_u32_e32 v50, vcc, 0x600000, v48
	s_nop 1
	v_addc_co_u32_e32 v51, vcc, 0, v49, vcc
	v_add_co_u32_e32 v52, vcc, 0x800000, v48
	s_nop 1
	v_addc_co_u32_e32 v53, vcc, 0, v49, vcc
	v_add_co_u32_e32 v54, vcc, 0xa00000, v48
	s_nop 1
	v_addc_co_u32_e32 v55, vcc, 0, v49, vcc
	v_add_co_u32_e32 v56, vcc, 0xc00000, v48
	s_nop 1
	v_addc_co_u32_e32 v57, vcc, 0, v49, vcc
	v_add_co_u32_e32 v58, vcc, 0xe00000, v48
	s_nop 1
	v_addc_co_u32_e32 v59, vcc, 0, v49, vcc
	v_add_co_u32_e32 v60, vcc, 0x1000000, v48
	s_nop 1
	v_addc_co_u32_e32 v61, vcc, 0, v49, vcc
	v_add_co_u32_e32 v62, vcc, 0x1200000, v48
	s_nop 1
	v_addc_co_u32_e32 v63, vcc, 0, v49, vcc
	v_add_co_u32_e32 v64, vcc, 0x1400000, v48
	s_nop 1
	v_addc_co_u32_e32 v65, vcc, 0, v49, vcc
	global_load_dwordx4 v[84:87], v[48:49], off
	global_load_dwordx4 v[88:91], v[16:17], off
	global_load_dwordx4 v[92:95], v[18:19], off
	global_load_dwordx4 v[96:99], v[50:51], off
	global_load_dwordx4 v[100:103], v[52:53], off
	global_load_dwordx4 v[104:107], v[54:55], off
	global_load_dwordx4 v[108:111], v[56:57], off
	global_load_dwordx4 v[112:115], v[58:59], off
	global_load_dwordx4 v[116:119], v[60:61], off
	global_load_dwordx4 v[120:123], v[62:63], off
	global_load_dwordx4 v[124:127], v[64:65], off
	global_load_dwordx4 v[74:77], v[24:25], off
	s_waitcnt vmcnt(0)
	v_pk_add_f32 v[78:79], v[84:85], 0 op_sel_hi:[1,0]
	v_pk_add_f32 v[80:81], v[86:87], 0 op_sel_hi:[1,0]
	v_pk_add_f32 v[78:79], v[78:79], v[88:89]
	v_pk_add_f32 v[80:81], v[80:81], v[90:91]
	v_pk_add_f32 v[78:79], v[78:79], v[92:93]
	v_pk_add_f32 v[80:81], v[80:81], v[94:95]
	v_pk_add_f32 v[78:79], v[78:79], v[96:97]
	v_pk_add_f32 v[80:81], v[80:81], v[98:99]
	v_pk_add_f32 v[78:79], v[78:79], v[100:101]
	v_pk_add_f32 v[80:81], v[80:81], v[102:103]
	v_pk_add_f32 v[78:79], v[78:79], v[104:105]
	v_pk_add_f32 v[80:81], v[80:81], v[106:107]
	v_pk_add_f32 v[78:79], v[78:79], v[108:109]
	v_pk_add_f32 v[80:81], v[80:81], v[110:111]
	v_pk_add_f32 v[78:79], v[78:79], v[112:113]
	v_pk_add_f32 v[80:81], v[80:81], v[114:115]
	v_pk_add_f32 v[78:79], v[78:79], v[116:117]
	v_pk_add_f32 v[80:81], v[80:81], v[118:119]
	v_pk_add_f32 v[78:79], v[78:79], v[120:121]
	v_pk_add_f32 v[80:81], v[80:81], v[122:123]
	v_pk_add_f32 v[78:79], v[78:79], v[124:125]
	v_pk_add_f32 v[80:81], v[80:81], v[126:127]
	v_pk_fma_f32 v[14:15], v[80:81], v[76:77], v[14:15]
	v_pk_fma_f32 v[12:13], v[78:79], v[74:75], v[12:13]
	global_load_dwordx4 v[84:87], v[48:49], off offset:1024
	global_load_dwordx4 v[88:91], v[16:17], off offset:1024
	global_load_dwordx4 v[92:95], v[18:19], off offset:1024
	global_load_dwordx4 v[96:99], v[50:51], off offset:1024
	global_load_dwordx4 v[100:103], v[52:53], off offset:1024
	global_load_dwordx4 v[104:107], v[54:55], off offset:1024
	global_load_dwordx4 v[108:111], v[56:57], off offset:1024
	global_load_dwordx4 v[112:115], v[58:59], off offset:1024
	global_load_dwordx4 v[116:119], v[60:61], off offset:1024
	global_load_dwordx4 v[120:123], v[62:63], off offset:1024
	global_load_dwordx4 v[124:127], v[64:65], off offset:1024
	global_load_dwordx4 v[74:77], v[26:27], off
	s_waitcnt vmcnt(0)
	v_pk_add_f32 v[78:79], v[86:87], 0 op_sel_hi:[1,0]
	v_pk_add_f32 v[80:81], v[84:85], 0 op_sel_hi:[1,0]
	v_pk_add_f32 v[78:79], v[78:79], v[90:91]
	v_pk_add_f32 v[80:81], v[80:81], v[88:89]
	v_pk_add_f32 v[78:79], v[78:79], v[94:95]
	v_pk_add_f32 v[80:81], v[80:81], v[92:93]
	v_pk_add_f32 v[78:79], v[78:79], v[98:99]
	v_pk_add_f32 v[80:81], v[80:81], v[96:97]
	v_pk_add_f32 v[78:79], v[78:79], v[102:103]
	v_pk_add_f32 v[80:81], v[80:81], v[100:101]
	v_pk_add_f32 v[78:79], v[78:79], v[106:107]
	v_pk_add_f32 v[80:81], v[80:81], v[104:105]
	v_pk_add_f32 v[78:79], v[78:79], v[110:111]
	v_pk_add_f32 v[80:81], v[80:81], v[108:109]
	v_pk_add_f32 v[78:79], v[78:79], v[114:115]
	v_pk_add_f32 v[80:81], v[80:81], v[112:113]
	v_pk_add_f32 v[78:79], v[78:79], v[118:119]
	v_pk_add_f32 v[80:81], v[80:81], v[116:117]
	v_pk_add_f32 v[78:79], v[78:79], v[122:123]
	v_pk_add_f32 v[80:81], v[80:81], v[120:121]
	v_pk_add_f32 v[78:79], v[78:79], v[126:127]
	v_pk_add_f32 v[80:81], v[80:81], v[124:125]
	v_pk_fma_f32 v[10:11], v[78:79], v[76:77], v[10:11]
	v_pk_fma_f32 v[8:9], v[80:81], v[74:75], v[8:9]
	global_load_dwordx4 v[84:87], v[48:49], off offset:2048
	global_load_dwordx4 v[88:91], v[16:17], off offset:2048
	global_load_dwordx4 v[92:95], v[18:19], off offset:2048
	global_load_dwordx4 v[96:99], v[50:51], off offset:2048
	global_load_dwordx4 v[100:103], v[52:53], off offset:2048
	global_load_dwordx4 v[104:107], v[54:55], off offset:2048
	global_load_dwordx4 v[108:111], v[56:57], off offset:2048
	global_load_dwordx4 v[112:115], v[58:59], off offset:2048
	global_load_dwordx4 v[116:119], v[60:61], off offset:2048
	global_load_dwordx4 v[120:123], v[62:63], off offset:2048
	global_load_dwordx4 v[124:127], v[64:65], off offset:2048
	global_load_dwordx4 v[74:77], v[28:29], off
	s_waitcnt vmcnt(0)
	v_pk_add_f32 v[78:79], v[86:87], 0 op_sel_hi:[1,0]
	v_pk_add_f32 v[80:81], v[84:85], 0 op_sel_hi:[1,0]
	v_pk_add_f32 v[78:79], v[78:79], v[90:91]
	v_pk_add_f32 v[80:81], v[80:81], v[88:89]
	v_pk_add_f32 v[78:79], v[78:79], v[94:95]
	v_pk_add_f32 v[80:81], v[80:81], v[92:93]
	v_pk_add_f32 v[78:79], v[78:79], v[98:99]
	v_pk_add_f32 v[80:81], v[80:81], v[96:97]
	v_pk_add_f32 v[78:79], v[78:79], v[102:103]
	v_pk_add_f32 v[80:81], v[80:81], v[100:101]
	v_pk_add_f32 v[78:79], v[78:79], v[106:107]
	v_pk_add_f32 v[80:81], v[80:81], v[104:105]
	v_pk_add_f32 v[78:79], v[78:79], v[110:111]
	v_pk_add_f32 v[80:81], v[80:81], v[108:109]
	v_pk_add_f32 v[78:79], v[78:79], v[114:115]
	v_pk_add_f32 v[80:81], v[80:81], v[112:113]
	v_pk_add_f32 v[78:79], v[78:79], v[118:119]
	v_pk_add_f32 v[80:81], v[80:81], v[116:117]
	v_pk_add_f32 v[78:79], v[78:79], v[122:123]
	v_pk_add_f32 v[80:81], v[80:81], v[120:121]
	v_pk_add_f32 v[78:79], v[78:79], v[126:127]
	v_pk_add_f32 v[80:81], v[80:81], v[124:125]
	v_pk_fma_f32 v[6:7], v[78:79], v[76:77], v[6:7]
	v_pk_fma_f32 v[4:5], v[80:81], v[74:75], v[4:5]
	global_load_dwordx4 v[84:87], v[48:49], off offset:3072
	global_load_dwordx4 v[88:91], v[16:17], off offset:3072
	global_load_dwordx4 v[92:95], v[18:19], off offset:3072
	global_load_dwordx4 v[96:99], v[50:51], off offset:3072
	global_load_dwordx4 v[100:103], v[52:53], off offset:3072
	global_load_dwordx4 v[104:107], v[54:55], off offset:3072
	global_load_dwordx4 v[108:111], v[56:57], off offset:3072
	global_load_dwordx4 v[112:115], v[58:59], off offset:3072
	global_load_dwordx4 v[116:119], v[60:61], off offset:3072
	global_load_dwordx4 v[120:123], v[62:63], off offset:3072
	global_load_dwordx4 v[124:127], v[64:65], off offset:3072
	global_load_dwordx4 v[16:19], v[30:31], off
	s_waitcnt vmcnt(0)
	v_pk_add_f32 v[48:49], v[86:87], 0 op_sel_hi:[1,0]
	v_pk_add_f32 v[78:79], v[84:85], 0 op_sel_hi:[1,0]
	v_pk_add_f32 v[48:49], v[48:49], v[90:91]
	v_pk_add_f32 v[74:75], v[78:79], v[88:89]
	global_store_dwordx4 v[46:47], v[12:15], off
	global_store_dwordx4 v[46:47], v[8:11], off offset:1024
	global_store_dwordx4 v[46:47], v[4:7], off offset:2048
	v_pk_add_f32 v[48:49], v[48:49], v[94:95]
	v_pk_add_f32 v[74:75], v[74:75], v[92:93]
	v_pk_add_f32 v[48:49], v[48:49], v[98:99]
	v_pk_add_f32 v[50:51], v[74:75], v[96:97]
	v_pk_add_f32 v[48:49], v[48:49], v[102:103]
	v_pk_add_f32 v[50:51], v[50:51], v[100:101]
	v_pk_add_f32 v[48:49], v[48:49], v[106:107]
	v_pk_add_f32 v[50:51], v[50:51], v[104:105]
	v_pk_add_f32 v[48:49], v[48:49], v[110:111]
	v_pk_add_f32 v[50:51], v[50:51], v[108:109]
	v_pk_add_f32 v[48:49], v[48:49], v[114:115]
	v_pk_add_f32 v[50:51], v[50:51], v[112:113]
	v_pk_add_f32 v[48:49], v[48:49], v[118:119]
	v_pk_add_f32 v[50:51], v[50:51], v[116:117]
	v_pk_add_f32 v[48:49], v[48:49], v[122:123]
	v_pk_add_f32 v[50:51], v[50:51], v[120:121]
	v_pk_add_f32 v[48:49], v[48:49], v[126:127]
	v_pk_add_f32 v[50:51], v[50:51], v[124:125]
	v_pk_fma_f32 v[2:3], v[48:49], v[18:19], v[2:3]
	v_pk_fma_f32 v[0:1], v[50:51], v[16:17], v[0:1]
	global_store_dwordx4 v[46:47], v[0:3], off offset:3072
	s_branch .LBB0_275
